# weight-transposition share of the in-proj workgroups reduced to 20 tiles each (rest done during out-proj), with the early copy-worker stop
# speedup vs baseline: 1.0048x; 1.0035x over previous
.Lwi_loop:
	s_addk_i32 s24, 0x37
	s_cmpk_lt_i32 s24, 0xc8c
	s_cbranch_scc0 .Lwi_lastB
	s_cmpk_lt_i32 s24, 0x1340
	s_cbranch_scc0 .Lwi_down_r
	s_sub_i32 s25, s24, 0x840
	s_and_b32 s26, s25, 31
	s_lshr_b32 s27, s25, 5
	s_lshl_b32 s28, s26, 6
	s_and_b32 s29, s27, 1
	s_mul_i32 s29, s29, 0x1600
	s_lshr_b32 s30, s27, 1
	s_lshl_b32 s30, s30, 7
	s_add_i32 s29, s29, s30
	s_mul_i32 s30, s28, 0x2c00
	s_add_i32 s30, s30, s29
	s_lshl_b32 s30, s30, 2
	s_add_u32 s34, s18, s30
	s_addc_u32 s35, s19, 0
	s_lshl_b32 s31, s27, 5
	s_add_i32 s31, s31, s26
	s_mov_b32 s33, 0xb000
	s_mov_b32 s46, 1
	s_mov_b32 s30, 0x2100000
	s_branch .Lwi_dec_r

.Lwi_nog_b1:
	ds_write_b32 v42, v20
	ds_write_b32 v42, v21 offset:4
	ds_write_b32 v42, v22 offset:8
	ds_write_b32 v42, v23 offset:12
	ds_write_b32 v42, v24 offset:8256
	ds_write_b32 v42, v25 offset:8260
	ds_write_b32 v42, v26 offset:8264
	ds_write_b32 v42, v27 offset:8268
	ds_write_b32 v42, v28 offset:16512
	ds_write_b32 v42, v29 offset:16516
	ds_write_b32 v42, v30 offset:16520
	ds_write_b32 v42, v31 offset:16524
	ds_write_b32 v42, v32 offset:24768
	ds_write_b32 v42, v33 offset:24772
	ds_write_b32 v42, v34 offset:24776
	ds_write_b32 v42, v35 offset:24780
	s_waitcnt lgkmcnt(0)
	s_barrier
	ds_read_b32 v54, v43
	ds_read_b32 v55, v43 offset:516
	ds_read_b32 v56, v43 offset:1032
	ds_read_b32 v57, v43 offset:1548
	ds_read_b32 v58, v43 offset:2064
	ds_read_b32 v59, v43 offset:2580
	ds_read_b32 v60, v43 offset:3096
	ds_read_b32 v61, v43 offset:3612
	ds_read_b32 v62, v43 offset:256
	ds_read_b32 v63, v43 offset:772
	ds_read_b32 v64, v43 offset:1288
	ds_read_b32 v65, v43 offset:1804
	ds_read_b32 v66, v43 offset:2320
	ds_read_b32 v67, v43 offset:2836
	ds_read_b32 v68, v43 offset:3352
	ds_read_b32 v69, v43 offset:3868
	s_waitcnt lgkmcnt(0)
	v_cvt_pk_bf16_f32 v72, v54, v55
	v_cvt_pk_bf16_f32 v73, v56, v57
	v_cvt_pk_bf16_f32 v74, v58, v59
	v_cvt_pk_bf16_f32 v75, v60, v61
	v_cvt_pk_bf16_f32 v76, v62, v63
	v_cvt_pk_bf16_f32 v77, v64, v65
	v_cvt_pk_bf16_f32 v78, v66, v67
	v_cvt_pk_bf16_f32 v79, v68, v69
	global_store_dwordx4 v44, v[72:75], s[48:49]
	global_store_dwordx4 v45, v[76:79], s[48:49]
	s_barrier
	s_addk_i32 s24, 0x37
	s_cmpk_lt_i32 s24, 0xc8c
	s_cbranch_scc0 .Lwi_lastA
	s_cmpk_lt_i32 s24, 0x1340
	s_cbranch_scc0 .Lwi_down_s
	s_sub_i32 s25, s24, 0x840
	s_and_b32 s26, s25, 31
	s_lshr_b32 s27, s25, 5
	s_lshl_b32 s28, s26, 6
	s_and_b32 s29, s27, 1
	s_mul_i32 s29, s29, 0x1600
	s_lshr_b32 s30, s27, 1
	s_lshl_b32 s30, s30, 7
	s_add_i32 s29, s29, s30
	s_mul_i32 s30, s28, 0x2c00
	s_add_i32 s30, s30, s29
	s_lshl_b32 s30, s30, 2
	s_add_u32 s34, s18, s30
	s_addc_u32 s35, s19, 0
	s_lshl_b32 s31, s27, 5
	s_add_i32 s31, s31, s26
	s_mov_b32 s33, 0xb000
	s_mov_b32 s47, 1
	s_mov_b32 s30, 0x2100000
	s_branch .Lwi_dec_s

.LBB0_1105:
	s_load_dword s3, s[0:1], 0xa8
	s_mov_b64 s[4:5], -1
	s_waitcnt lgkmcnt(0)
	s_addk_i32 s3, 0xffb0
	s_cmp_lt_i32 s2, s3
	s_cbranch_scc1 .LBB0_1127
	s_cmpk_lt_i32 s2, 0xf0
	s_cbranch_scc0 .Lwt_skip
	s_load_dwordx2 s[18:19], s[0:1], 0x68
	s_load_dwordx2 s[20:21], s[0:1], 0x60
	s_load_dwordx2 s[22:23], s[0:1], 0x80
	s_mov_b64 exec, -1
	s_sub_i32 s24, s2, 0xb0
	s_addk_i32 s24, 0xc8c
	v_lshrrev_b32_e32 v40, 5, v156
	v_and_b32_e32 v41, 31, v156
	v_lshlrev_b32_e32 v41, 4, v41
	v_mul_u32_u24_e32 v42, 0x204, v40
	v_add_u32_e32 v42, v42, v41
	v_and_b32_e32 v43, 7, v156
	v_mul_u32_u24_e32 v43, 0x1020, v43
	v_lshrrev_b32_e32 v51, 3, v156
	v_lshl_add_u32 v43, v51, 2, v43
	v_lshrrev_b32_e32 v44, 4, v51
	v_lshlrev_b32_e32 v44, 1, v44
	v_bfe_u32 v52, v156, 2, 1
	v_add_u32_e32 v44, v44, v52
	v_lshlrev_b32_e32 v44, 10, v44
	v_and_b32_e32 v52, 15, v51
	v_lshlrev_b32_e32 v52, 6, v52
	v_and_b32_e32 v53, 3, v156
	v_lshl_add_u32 v52, v53, 4, v52
	v_and_b32_e32 v53, 8, v51
	v_lshlrev_b32_e32 v53, 2, v53
	v_xor_b32_e32 v52, v52, v53
	v_add_u32_e32 v44, v44, v52
	v_add_u32_e32 v45, 0x2000, v44
	v_lshlrev_b32_e32 v50, 2, v40
	s_waitcnt lgkmcnt(0)
	s_cmpk_lt_i32 s24, 0x1340
	s_cbranch_scc0 .Lwt_down_p
	s_sub_i32 s25, s24, 0x840
	s_and_b32 s26, s25, 31
	s_lshr_b32 s27, s25, 5
	s_lshl_b32 s28, s26, 6
	s_and_b32 s29, s27, 1
	s_mul_i32 s29, s29, 0x1600
	s_lshr_b32 s30, s27, 1
	s_lshl_b32 s30, s30, 7
	s_add_i32 s29, s29, s30
	s_mul_i32 s30, s28, 0x2c00
	s_add_i32 s30, s30, s29
	s_lshl_b32 s30, s30, 2
	s_add_u32 s34, s18, s30
	s_addc_u32 s35, s19, 0
	s_lshl_b32 s31, s27, 5
	s_add_i32 s31, s31, s26
	s_mov_b32 s33, 0xb000
	s_mov_b32 s46, 1
	s_mov_b32 s30, 0x2100000
	s_branch .Lwt_dec_p
